# v6 + P1 sample-row Z mini GEMM: 24 laddered operand loads hoisted to issue with the first 12 (fresh registers), single wait
# baseline (speedup 1.0000x reference)
;     ...
;     for (int u = (int)((blockIdx.x + rot) % G); u < n_rb * NSUB * ncu; u += G) {
;         const int cu = u % ncu, t_ = u / ncu, rowb = row0 + (t_ / NSUB) * 128 + (t_ % NSUB) * (16 * NRB);
;         const bf16* ap = A + (size_t)(rowb + l15) * K + wave * (K >> 3) + quad * 8;
;         const int brow = TWO ? ((16 * cu) >> 7) * 256 + ((16 * cu) & 127) : 16 * cu;
;         const bf16* bp = Bt + (size_t)(brow + l15) * K + wave * (K >> 3) + quad * 8;
;         f32x4 acc0[NRB], acc1[NRB];
; #pragma unroll
;         for (int r = 0; r < NRB; ++r) { acc0[r] = (f32x4){0.f, 0.f, 0.f, 0.f}; acc1[r] = (f32x4){0.f, 0.f, 0.f, 0.f}; }
;         constexpr int KS = TWO ? 2 : (NRB == 8 ? 4 : 12);
;         for (int s0 = 0; s0 < nsw; s0 += KS) {
;             bf16x8 a[KS][NRB], b[KS], c[KS];
; #pragma unroll
;             for (int s = 0; s < KS; ++s) { const bool on = s0 + s < nsw; const int ko = (s0 + s) * 32;
;                 b[s] = on ? *(const bf16x8*)(bp + ko) : (bf16x8){0, 0, 0, 0, 0, 0, 0, 0}; if (TWO) c[s] = on ? *(const bf16x8*)(bp + (size_t)128 * K + ko) : (bf16x8){0, 0, 0, 0, 0, 0, 0, 0};
; #pragma unroll
;                 for (int r = 0; r < NRB; ++r) a[s][r] = on ? *(const bf16x8*)(ap + (size_t)(16 * r) * K + ko) : (bf16x8){0, 0, 0, 0, 0, 0, 0, 0}; }
; #pragma unroll
;             for (int s = 0; s < KS; ++s)
; #pragma unroll
;                 for (int r = 0; r < NRB; ++r) { acc0[r] = __builtin_amdgcn_mfma_f32_16x16x32_bf16(b[s], a[s][r], acc0[r], 0, 0, 0); if (TWO) acc1[r] = __builtin_amdgcn_mfma_f32_16x16x32_bf16(c[s], a[s][r], acc1[r], 0, 0, 0); }
.LBB0_188:
	s_ashr_i32 s0, s10, 31
	s_lshr_b32 s0, s0, 23
	s_add_i32 s0, s10, s0
	s_ashr_i32 s0, s0, 9
	s_lshl_b32 s17, s0, 7
	s_addk_i32 s17, 0x4000
	v_or_b32_e32 v4, s17, v144
	v_ashrrev_i32_e32 v5, 31, v4
	s_lshl_b32 s18, s0, 13
	v_lshlrev_b64 v[4:5], 11, v[4:5]
	s_sub_i32 s0, s11, s18
	v_add_u32_e32 v6, s0, v144
	v_lshl_add_u64 v[66:67], v[0:1], 0, v[4:5]
	s_mov_b32 s0, 0x8000
	v_add_co_u32_e64 v68, s[0:1], s0, v66
	v_ashrrev_i32_e32 v7, 31, v6
	s_nop 0
	v_addc_co_u32_e64 v69, s[0:1], 0, v67, s[0:1]
	s_mov_b32 s0, 0x10000
	s_nop 0
	v_add_co_u32_e64 v70, s[0:1], s0, v66
	v_lshlrev_b64 v[6:7], 11, v[6:7]
	s_nop 0
	v_addc_co_u32_e64 v71, s[0:1], 0, v67, s[0:1]
	s_mov_b32 s0, 0x18000
	s_nop 0
	v_add_co_u32_e64 v72, s[0:1], s0, v66
	s_mov_b32 s4, 0x28000
	s_nop 0
	v_addc_co_u32_e64 v73, s[0:1], 0, v67, s[0:1]
	s_mov_b32 s0, 0x20000
	v_lshl_add_u64 v[64:65], v[2:3], 0, v[6:7]
	v_add_co_u32_e64 v74, s[0:1], s0, v66
	v_add_co_u32_e64 v6, s[4:5], s4, v66
	global_load_dwordx4 v[12:15], v[64:65], off
	global_load_dwordx4 v[48:51], v[64:65], off offset:64
	v_addc_co_u32_e64 v75, s[0:1], 0, v67, s[0:1]
	v_addc_co_u32_e64 v7, s[0:1], 0, v67, s[4:5]
	s_mov_b32 s6, 0x30000
	s_mov_b32 s0, 0x38000
	v_add_co_u32_e64 v4, s[6:7], s6, v66
	v_add_co_u32_e64 v76, s[0:1], s0, v66
	s_nop 0
	v_addc_co_u32_e64 v5, s[4:5], 0, v67, s[6:7]
	v_addc_co_u32_e64 v77, s[0:1], 0, v67, s[0:1]
	global_load_dwordx4 v[16:19], v[66:67], off
	global_load_dwordx4 v[20:23], v[68:69], off
	global_load_dwordx4 v[24:27], v[70:71], off
	global_load_dwordx4 v[56:59], v[68:69], off offset:64
	global_load_dwordx4 v[28:31], v[72:73], off
	global_load_dwordx4 v[32:35], v[74:75], off
	global_load_dwordx4 v[36:39], v[6:7], off
	global_load_dwordx4 v[40:43], v[4:5], off
	global_load_dwordx4 v[44:47], v[76:77], off
	global_load_dwordx4 v[52:55], v[66:67], off offset:64
	global_load_dwordx4 v[96:99], v[70:71], off offset:64
	global_load_dwordx4 v[100:103], v[74:75], off offset:64
	global_load_dwordx4 v[112:115], v[6:7], off offset:64
	global_load_dwordx4 v[116:119], v[72:73], off offset:64
	global_load_dwordx4 v[120:123], v[4:5], off offset:64
	global_load_dwordx4 v[152:155], v[76:77], off offset:64
	global_load_dwordx4 v[168:171], v[64:65], off offset:128
	global_load_dwordx4 v[172:175], v[66:67], off offset:128
	global_load_dwordx4 v[176:179], v[68:69], off offset:128
	global_load_dwordx4 v[180:183], v[70:71], off offset:128
	global_load_dwordx4 v[184:187], v[74:75], off offset:128
	global_load_dwordx4 v[188:191], v[6:7], off offset:128
	global_load_dwordx4 v[192:195], v[72:73], off offset:128
	global_load_dwordx4 v[196:199], v[4:5], off offset:128
	global_load_dwordx4 v[200:203], v[64:65], off offset:192
	global_load_dwordx4 v[204:207], v[76:77], off offset:128
	global_load_dwordx4 v[208:211], v[66:67], off offset:192
	global_load_dwordx4 v[212:215], v[68:69], off offset:192
	global_load_dwordx4 v[216:219], v[70:71], off offset:192
	global_load_dwordx4 v[220:223], v[6:7], off offset:192
	global_load_dwordx4 v[224:227], v[4:5], off offset:192
	global_load_dwordx4 v[228:231], v[72:73], off offset:192
	global_load_dwordx4 v[232:235], v[74:75], off offset:192
	global_load_dwordx4 v[240:243], v[76:77], off offset:192
	s_waitcnt vmcnt(24)
	v_mfma_f32_16x16x32_bf16 v[16:19], v[12:15], v[16:19], 0
	v_mfma_f32_16x16x32_bf16 v[20:23], v[12:15], v[20:23], 0
	v_mfma_f32_16x16x32_bf16 v[24:27], v[12:15], v[24:27], 0
	v_mfma_f32_16x16x32_bf16 v[28:31], v[12:15], v[28:31], 0
	v_mfma_f32_16x16x32_bf16 v[32:35], v[12:15], v[32:35], 0
	v_mfma_f32_16x16x32_bf16 v[36:39], v[12:15], v[36:39], 0
	v_mfma_f32_16x16x32_bf16 v[40:43], v[12:15], v[40:43], 0
	v_mfma_f32_16x16x32_bf16 v[12:15], v[12:15], v[44:47], 0
	s_nop 0
	v_mfma_f32_16x16x32_bf16 v[20:23], v[48:51], v[56:59], v[20:23]
	s_nop 0
	s_waitcnt vmcnt(0)
	v_mfma_f32_16x16x32_bf16 v[24:27], v[48:51], v[96:99], v[24:27]
	s_nop 0
	v_mfma_f32_16x16x32_bf16 v[16:19], v[48:51], v[52:55], v[16:19]
	s_nop 0
	s_nop 0
	v_mfma_f32_16x16x32_bf16 v[32:35], v[48:51], v[100:103], v[32:35]
	s_nop 0
	v_mfma_f32_16x16x32_bf16 v[28:31], v[48:51], v[116:119], v[28:31]
	s_nop 0
	s_nop 0
	s_nop 0
	v_mfma_f32_16x16x32_bf16 v[36:39], v[48:51], v[112:115], v[36:39]
	s_nop 0
	s_nop 0
	v_mfma_f32_16x16x32_bf16 v[40:43], v[48:51], v[120:123], v[40:43]
	s_nop 0
	s_nop 0
	v_mfma_f32_16x16x32_bf16 v[12:15], v[48:51], v[152:155], v[12:15]
	s_nop 0
	s_nop 0
	v_mfma_f32_16x16x32_bf16 v[20:23], v[168:171], v[176:179], v[20:23]
	s_nop 0
	s_nop 0
	v_mfma_f32_16x16x32_bf16 v[24:27], v[168:171], v[180:183], v[24:27]
	s_nop 0
	v_mfma_f32_16x16x32_bf16 v[16:19], v[168:171], v[172:175], v[16:19]
	s_nop 0
	s_nop 0
	v_mfma_f32_16x16x32_bf16 v[32:35], v[168:171], v[184:187], v[32:35]
	s_nop 0
	v_mfma_f32_16x16x32_bf16 v[28:31], v[168:171], v[192:195], v[28:31]
	s_nop 0
	s_nop 0
	s_nop 0
	v_mfma_f32_16x16x32_bf16 v[36:39], v[168:171], v[188:191], v[36:39]
	s_nop 0
	s_nop 0
	v_mfma_f32_16x16x32_bf16 v[40:43], v[168:171], v[196:199], v[40:43]
	s_nop 0
	s_nop 0
	v_mfma_f32_16x16x32_bf16 v[12:15], v[168:171], v[204:207], v[12:15]
	s_nop 0
	s_nop 0
	v_mfma_f32_16x16x32_bf16 v[24:27], v[200:203], v[216:219], v[24:27]
	s_nop 0
	s_nop 0
	s_nop 0
	v_mfma_f32_16x16x32_bf16 v[16:19], v[200:203], v[208:211], v[16:19]
	s_nop 0
	v_mfma_f32_16x16x32_bf16 v[20:23], v[200:203], v[212:215], v[20:23]
	s_nop 0
	s_nop 4
	ds_write_b128 v11, v[16:19]
	s_nop 0
	v_mfma_f32_16x16x32_bf16 v[32:35], v[200:203], v[232:235], v[32:35]
	s_nop 0
	v_mfma_f32_16x16x32_bf16 v[16:19], v[200:203], v[220:223], v[36:39]
	v_mfma_f32_16x16x32_bf16 v[28:31], v[200:203], v[228:231], v[28:31]
	ds_write_b128 v11, v[20:23] offset:1024
	ds_write_b128 v11, v[24:27] offset:2048
	s_nop 5
	ds_write_b128 v11, v[28:31] offset:3072
	v_mfma_f32_16x16x32_bf16 v[4:7], v[200:203], v[224:227], v[40:43]
	ds_write_b128 v11, v[32:35] offset:4096
	ds_write_b128 v11, v[16:19] offset:5120
	s_nop 5
	ds_write_b128 v11, v[4:7] offset:6144
	s_nop 0
	v_mfma_f32_16x16x32_bf16 v[4:7], v[200:203], v[240:243], v[12:15]
	s_nop 7
	ds_write_b128 v11, v[4:7] offset:7168
	v_mov_b32_e32 v6, 0
	v_mov_b32_e32 v7, 0
	v_mov_b32_e32 v4, 0
	v_mov_b32_e32 v5, 0
	s_waitcnt lgkmcnt(0)
	s_barrier
;     ...
;         for (int r = 0; r < NRB; ++r) red[(wave * NRB + r) * 64 + lane] = acc0[r];
;         __syncthreads();
;         if (wave < NRB) {
; #pragma unroll
;             for (int s = 0; s < 8; ++s) t0 += red[(s * NRB + wave) * 64 + lane]; }
	s_and_saveexec_b64 s[0:1], vcc
	s_cbranch_execz .LBB0_190
	ds_read_b128 v[4:7], v8
	s_waitcnt lgkmcnt(0)
	v_pk_add_f32 v[12:13], v[6:7], 0 op_sel_hi:[1,0]
	v_pk_add_f32 v[14:15], v[4:5], 0 op_sel_hi:[1,0]
	ds_read_b128 v[4:7], v8 offset:8192
	s_waitcnt lgkmcnt(0)
	v_pk_add_f32 v[12:13], v[12:13], v[6:7]
	v_pk_add_f32 v[14:15], v[14:15], v[4:5]
	ds_read_b128 v[4:7], v8 offset:16384
	s_waitcnt lgkmcnt(0)
	v_pk_add_f32 v[12:13], v[12:13], v[6:7]
	v_pk_add_f32 v[14:15], v[14:15], v[4:5]
	ds_read_b128 v[4:7], v8 offset:24576
	s_waitcnt lgkmcnt(0)
	v_pk_add_f32 v[12:13], v[12:13], v[6:7]
	v_pk_add_f32 v[14:15], v[14:15], v[4:5]
	ds_read_b128 v[4:7], v8 offset:32768
	s_waitcnt lgkmcnt(0)
	v_pk_add_f32 v[12:13], v[12:13], v[6:7]
	v_pk_add_f32 v[14:15], v[14:15], v[4:5]
	ds_read_b128 v[4:7], v8 offset:40960
	s_waitcnt lgkmcnt(0)
	v_pk_add_f32 v[12:13], v[12:13], v[6:7]
	v_pk_add_f32 v[14:15], v[14:15], v[4:5]
	ds_read_b128 v[4:7], v8 offset:49152
	s_waitcnt lgkmcnt(0)
	v_pk_add_f32 v[6:7], v[12:13], v[6:7]
	v_pk_add_f32 v[16:17], v[14:15], v[4:5]
	ds_read_b128 v[12:15], v8 offset:57344
	s_waitcnt lgkmcnt(0)
	v_pk_add_f32 v[4:5], v[6:7], v[14:15]
	v_pk_add_f32 v[6:7], v[16:17], v[12:13]

; __global__ void __launch_bounds__(512, 2) fwd_mega(Args a) {
;     extern __shared__ __attribute__((aligned(16))) unsigned char lds_raw[];
	.amdhsa_kernel _Z8fwd_mega4Args
		.amdhsa_group_segment_fixed_size 0
		.amdhsa_private_segment_fixed_size 0
		.amdhsa_kernarg_size 472
		.amdhsa_user_sgpr_count 2
		.amdhsa_user_sgpr_dispatch_ptr 0
		.amdhsa_user_sgpr_queue_ptr 0
		.amdhsa_user_sgpr_kernarg_segment_ptr 1
		.amdhsa_user_sgpr_dispatch_id 0
		.amdhsa_user_sgpr_kernarg_preload_length 0
		.amdhsa_user_sgpr_kernarg_preload_offset 0
		.amdhsa_user_sgpr_private_segment_size 0
		.amdhsa_uses_dynamic_stack 0
		.amdhsa_enable_private_segment 0
		.amdhsa_system_sgpr_workgroup_id_x 1
		.amdhsa_system_sgpr_workgroup_id_y 0
		.amdhsa_system_sgpr_workgroup_id_z 0
		.amdhsa_system_sgpr_workgroup_info 0
		.amdhsa_system_vgpr_workitem_id 2
		.amdhsa_next_free_vgpr 256
		.amdhsa_next_free_sgpr 98
		.amdhsa_accum_offset 256
		.amdhsa_reserve_vcc 1
		.amdhsa_float_round_mode_32 0
		.amdhsa_float_round_mode_16_64 0
		.amdhsa_float_denorm_mode_32 3
		.amdhsa_float_denorm_mode_16_64 3
		.amdhsa_dx10_clamp 1
		.amdhsa_ieee_mode 1
		.amdhsa_fp16_overflow 0
		.amdhsa_tg_split 0
		.amdhsa_exception_fp_ieee_invalid_op 0
		.amdhsa_exception_fp_denorm_src 0
		.amdhsa_exception_fp_ieee_div_zero 0
		.amdhsa_exception_fp_ieee_overflow 0
		.amdhsa_exception_fp_ieee_underflow 0
		.amdhsa_exception_fp_ieee_inexact 0
		.amdhsa_exception_int_div_zero 0
	.end_amdhsa_kernel

; __global__ void __launch_bounds__(512, 2) fwd_mega(Args a) {
;     extern __shared__ __attribute__((aligned(16))) unsigned char lds_raw[];
amdhsa.kernels:
  - .agpr_count:     0
    .args:
      - .offset:         0
        .size:           216
        .value_kind:     by_value
      - .offset:         216
        .size:           4
        .value_kind:     hidden_block_count_x
      - .offset:         220
        .size:           4
        .value_kind:     hidden_block_count_y
      - .offset:         224
        .size:           4
        .value_kind:     hidden_block_count_z
      - .offset:         228
        .size:           2
        .value_kind:     hidden_group_size_x
      - .offset:         230
        .size:           2
        .value_kind:     hidden_group_size_y
      - .offset:         232
        .size:           2
        .value_kind:     hidden_group_size_z
      - .offset:         234
        .size:           2
        .value_kind:     hidden_remainder_x
      - .offset:         236
        .size:           2
        .value_kind:     hidden_remainder_y
      - .offset:         238
        .size:           2
        .value_kind:     hidden_remainder_z
      - .offset:         256
        .size:           8
        .value_kind:     hidden_global_offset_x
      - .offset:         264
        .size:           8
        .value_kind:     hidden_global_offset_y
      - .offset:         272
        .size:           8
        .value_kind:     hidden_global_offset_z
      - .offset:         280
        .size:           2
        .value_kind:     hidden_grid_dims
      - .offset:         304
        .size:           8
        .value_kind:     hidden_multigrid_sync_arg
      - .offset:         336
        .size:           4
        .value_kind:     hidden_dynamic_lds_size
    .group_segment_fixed_size: 0
    .kernarg_segment_align: 8
    .kernarg_segment_size: 472
    .language:       OpenCL C
    .language_version:
      - 2
      - 0
    .max_flat_workgroup_size: 512
    .name:           _Z8fwd_mega4Args
    .private_segment_fixed_size: 0
    .sgpr_count:     104
    .sgpr_spill_count: 81
    .symbol:         _Z8fwd_mega4Args.kd
    .uniform_work_group_size: 1
    .uses_dynamic_stack: false
    .vgpr_count:     256
    .vgpr_spill_count: 0
    .wavefront_size: 64
